# v82 + phase-4 lag (~10.5 us) of workgroups without a GLU tile, which meanwhile prefetch their partner's SG tile into L2
# speedup vs baseline: 1.0167x; 1.0167x over previous
.LBB0_589:
	s_cmp_gt_i32 s26, 4
	s_cselect_b64 s[4:5], -1, 0
	s_xor_b64 s[0:1], s[0:1], -1
	s_or_b64 s[0:1], s[4:5], s[0:1]
	s_and_b64 vcc, exec, s[0:1]
	s_cbranch_vccnz .LBB0_771
	s_cmpk_lt_u32 s96, 0x80
	s_cbranch_scc1 .Lp4_lag
	s_sleep 127
	s_and_b32 s98, s96, 7
	s_lshl_b32 s98, s98, 3
	s_bfe_u32 s99, s96, 0x30003
	s_or_b32 s98, s98, s99
	s_lshl_b32 s98, s98, 18
	s_bfe_u32 s99, s96, 0x10006
	s_lshl_b32 s99, s99, 9
	s_or_b32 s98, s98, s99
	s_add_u32 s100, s78, 0x5600000
	s_addc_u32 s101, s79, 0
	s_add_u32 s100, s100, s98
	s_addc_u32 s101, s101, 0
	v_and_b32_e32 v152, 0x3ff, v0
	v_lshrrev_b32_e32 v153, 1, v152
	v_and_b32_e32 v152, 1, v152
	v_lshlrev_b32_e32 v152, 8, v152
	v_lshl_or_b32 v153, v153, 10, v152
	global_load_dword v154, v153, s[100:101]
	global_load_dword v155, v153, s[100:101] offset:128
	s_sleep 127
	s_sleep 127
	s_waitcnt vmcnt(0)
